# p3scanbal: P3's SSD state scan is done by the 192 LoRA blocks only; the K/V GEMM blocks (measured long pole, zero slack) skip it
# baseline (speedup 1.0000x reference)
.LBB0_583:
	s_mov_b32 s98, s69
	s_mov_b32 s99, s96
	s_cmpk_lg_i32 s96, 0x100
	s_cbranch_scc1 .Lss_go
	s_cmp_lt_u32 s69, 64
	s_cbranch_scc1 .LBB0_589
	s_sub_i32 s69, s69, 64
	s_movk_i32 s96, 0xc0

.LBB0_588:
	s_or_b64 exec, exec, s[0:1]
	s_mov_b32 s69, s98
	s_mov_b32 s96, s99
